# conversion rebalancing: 1024 (layers 1-2) / 512 (layer 0) more next-layer items converted in the FFN-up idle half round instead of the FFN-down tail
# baseline (speedup 1.0000x reference)
; __device__ __forceinline__ PItem p0_decode(const Args& a, int it) {
;     constexpr int I_IN = 16 * 96, I_OUT = 16 * 32, I_W1 = 16 * 88, I_W2 = 44 * 32, I_LAYER = I_IN + I_OUT + 2 * I_W1 + I_W2;
;     const int l = it / I_LAYER, e = l >> 1, odd = l & 1; int r = it % I_LAYER;
;     unsigned char* wl = a.ws + WS_W + (size_t)l * W_LAYER; float* cv = (float*)(a.ws + WS_CVEC) + (size_t)l * CVEC_LAYER;
;     PItem p;
;     if (r < I_IN) { const int kb = r / 96, nb = r % 96; p.W = (odd ? a.in[13] : a.in[5]) + (size_t)e * D * EIN; p.N = EIN; p.K = D; p.g = l > 0 ? a.in[21] + (size_t)(l - 1) * D : nullptr; p.be = l > 0 ? a.in[22] + (size_t)(l - 1) * D : nullptr;
;         p.WT = (bf16*)(wl + W_IN); p.drow0 = in_dst_row(32 * nb, odd); p.k0 = 64 * kb; p.n0 = 32 * nb; p.c1 = cv; p.c2 = cv + EIN; return p; } r -= I_IN;
;     if (r < I_OUT) { const int kb = r / 32, nb = r % 32; p.W = (odd ? a.in[15] : a.in[6]) + (size_t)e * D * D; p.N = D; p.K = D; p.g = nullptr; p.be = nullptr;
;         p.WT = (bf16*)(wl + W_OUT); p.drow0 = 32 * nb; p.k0 = 64 * kb; p.n0 = 32 * nb; p.c1 = nullptr; p.c2 = nullptr; return p; } r -= I_OUT;
;     if (r < 2 * I_W1) { const int second = r >= I_W1; if (second) r -= I_W1; const int kb = r / 88, nb = r % 88, n0 = 32 * nb; p.W = (second ? a.in[17] : a.in[16]) + (size_t)l * D * DFF; p.N = DFF; p.K = D;
;         p.g = a.in[19] + (size_t)l * D; p.be = a.in[20] + (size_t)l * D; p.WT = (bf16*)(wl + W_13); p.drow0 = 256 * (n0 >> 7) + (second ? 128 : 0) + (n0 & 127); p.k0 = 64 * kb; p.n0 = n0; p.c1 = cv + 2 * EIN; p.c2 = cv + 2 * EIN + NUP; return p; } r -= 2 * I_W1;
; __global__ void __launch_bounds__(NWAVES * 64, 2) mk_fwd(Args args) {
;     ...
;             if (F.G == 256 && (int)blockIdx.x >= 128) { const int wi = (int)blockIdx.x - 128;
;                 if (l == 0) p_convert_tail(F, args, P_ILAYER - P_IW2, P_ILAYER, wi, 128);
;                 if (l < 3) { const int xs = (l == 0) ? 768 : 1792; p_convert_tail(F, args, (l + 2) * P_ILAYER - xs, (l + 2) * P_ILAYER, wi, 128); } }
.LBB0_1294:
	v_readlane_b32 s0, v255, 62
	s_cmp_eq_u32 s0, 3
	v_readlane_b32 s1, v255, 63
	s_cbranch_scc1 .LBB0_1348
	v_readlane_b32 s0, v255, 53
	v_readlane_b32 s1, v255, 54
	s_and_b64 s[0:1], s[0:1], exec
	v_readlane_b32 s10, v255, 62
	s_movk_i32 s0, 0xfb00
	s_mul_i32 s7, s10, 0x1880
	s_cselect_b32 s0, s0, 0xfffff500
	s_addk_i32 s7, 0x3100
	v_readlane_b32 s1, v253, 59
	s_add_i32 s1, s1, s7
	v_mbcnt_lo_u32_b32 v0, -1, 0
	v_mbcnt_hi_u32_b32 v0, -1, v0
	s_add_i32 s13, s1, s0
	v_add_u32_e32 v0, s75, v0
	s_cmp_ge_i32 s13, s7
	v_readlane_b32 s11, v255, 63
	s_cbranch_scc1 .LBB0_1348
	s_mul_hi_i32 s0, s13, 0x5397829d
	s_lshr_b32 s1, s0, 31
	s_ashr_i32 s0, s0, 11
	s_add_i32 s30, s0, s1
	s_mul_i32 s1, s30, 0x1880
	s_ashr_i32 s34, s30, 1
	s_and_b32 s0, s30, 1
	s_sub_i32 s1, s13, s1
	s_ashr_i32 s31, s30, 31
	s_mul_i32 s10, s30, 0x1880000
	v_readlane_b32 s11, v253, 5
	s_mul_hi_i32 s2, s30, 0x1880000
	s_add_u32 s22, s11, s10
	v_readlane_b32 s10, v253, 6
	s_addc_u32 s23, s10, s2
	s_mul_i32 s10, s30, 0x11000
	v_readlane_b32 s11, v253, 7
	s_mul_hi_i32 s2, s30, 0x11000
	s_add_u32 s26, s11, s10
	v_readlane_b32 s10, v253, 8
	s_addc_u32 s27, s10, s2
	s_cmpk_gt_i32 s1, 0x5ff
	s_mov_b64 s[48:49], -1
	s_cbranch_scc0 .LBB0_1305
	s_cmpk_gt_u32 s1, 0x7ff
	s_cbranch_scc0 .LBB0_1302
	s_mov_b64 s[18:19], -1
	s_cmpk_gt_u32 s1, 0x12ff
	s_mul_hi_i32 s2, s30, 0xb00000
	s_mul_i32 s17, s30, 0xb00000
	s_cbranch_scc0 .LBB0_1300
	v_readlane_b32 s56, v253, 26
	v_readlane_b32 s57, v253, 27
	s_add_u32 s10, s56, s17
	s_addc_u32 s11, s57, s2
	s_add_u32 s14, s22, 0x1300000
	s_addc_u32 s15, s23, 0
	s_lshl_b32 s16, s1, 1
	s_lshl_b32 s12, s1, 5
	s_and_b32 s16, s16, 0x7fffffc0
	v_readlane_b32 s58, v253, 28
	v_readlane_b32 s59, v253, 29
	v_readlane_b32 s60, v253, 30
	v_readlane_b32 s61, v253, 31
	v_readlane_b32 s62, v253, 32
	v_readlane_b32 s63, v253, 33
	s_and_b32 s12, s12, 0x3e0
	s_addk_i32 s16, 0xda00
	s_mov_b64 s[18:19], 0

; __device__ __forceinline__ PItem p0_decode(const Args& a, int it) {
;     constexpr int I_IN = 16 * 96, I_OUT = 16 * 32, I_W1 = 16 * 88, I_W2 = 44 * 32, I_LAYER = I_IN + I_OUT + 2 * I_W1 + I_W2;
;     const int l = it / I_LAYER, e = l >> 1, odd = l & 1; int r = it % I_LAYER;
;     unsigned char* wl = a.ws + WS_W + (size_t)l * W_LAYER; float* cv = (float*)(a.ws + WS_CVEC) + (size_t)l * CVEC_LAYER;
;     PItem p;
;     if (r < I_IN) { const int kb = r / 96, nb = r % 96; p.W = (odd ? a.in[13] : a.in[5]) + (size_t)e * D * EIN; p.N = EIN; p.K = D; p.g = l > 0 ? a.in[21] + (size_t)(l - 1) * D : nullptr; p.be = l > 0 ? a.in[22] + (size_t)(l - 1) * D : nullptr;
;         p.WT = (bf16*)(wl + W_IN); p.drow0 = in_dst_row(32 * nb, odd); p.k0 = 64 * kb; p.n0 = 32 * nb; p.c1 = cv; p.c2 = cv + EIN; return p; } r -= I_IN;
;     if (r < I_OUT) { const int kb = r / 32, nb = r % 32; p.W = (odd ? a.in[15] : a.in[6]) + (size_t)e * D * D; p.N = D; p.K = D; p.g = nullptr; p.be = nullptr;
;         p.WT = (bf16*)(wl + W_OUT); p.drow0 = 32 * nb; p.k0 = 64 * kb; p.n0 = 32 * nb; p.c1 = nullptr; p.c2 = nullptr; return p; } r -= I_OUT;
;     if (r < 2 * I_W1) { const int second = r >= I_W1; if (second) r -= I_W1; const int kb = r / 88, nb = r % 88, n0 = 32 * nb; p.W = (second ? a.in[17] : a.in[16]) + (size_t)l * D * DFF; p.N = DFF; p.K = D;
;         p.g = a.in[19] + (size_t)l * D; p.be = a.in[20] + (size_t)l * D; p.WT = (bf16*)(wl + W_13); p.drow0 = 256 * (n0 >> 7) + (second ? 128 : 0) + (n0 & 127); p.k0 = 64 * kb; p.n0 = n0; p.c1 = cv + 2 * EIN; p.c2 = cv + 2 * EIN + NUP; return p; } r -= 2 * I_W1;
; __global__ void __launch_bounds__(NWAVES * 64, 2) mk_fwd(Args args) {
;     ...
;                   if (l < 3) { if (mfirst > 0) { if ((int)blockIdx.x < mfirst) { p_convert_tail(F, args, (l + 1) * P_ILAYER, (l + 2) * P_ILAYER - ((F.G == 256) ? (l == 0 ? 768 : 1792) : 0), (int)blockIdx.x, mfirst); if (l == 0) p_state_copies_tail(F, args, (int)blockIdx.x, mfirst); } }
;                   else { p_convert_tail(F, args, (l + 1) * P_ILAYER, (l + 2) * P_ILAYER - ((F.G == 256) ? (l == 0 ? 768 : 1792) : 0), (int)blockIdx.x, F.G); if (l == 0) p_state_copies_tail(F, args, (int)blockIdx.x, F.G); } } } }
.LBB0_1546:
	s_waitcnt vmcnt(0)
	s_barrier
	v_readlane_b32 s0, v255, 62
	s_cmp_lg_u32 s0, 3
	s_mov_b64 s[10:11], -1
	v_readlane_b32 s1, v255, 63
	s_cbranch_scc0 .LBB0_1764
	s_cmp_lt_i32 s29, 33
	s_cbranch_scc0 .LBB0_1627
	v_readlane_b32 s0, v255, 62
	v_readlane_b32 s1, v255, 63
	s_mul_i32 s2, s0, 0x1880
	v_readlane_b32 s0, v255, 53
	v_readlane_b32 s1, v255, 54
	s_and_b64 s[0:1], s[0:1], exec
	s_movk_i32 s0, 0xfb00
	s_cselect_b32 s7, s0, 0xfffff500
	v_readlane_b32 s0, v252, 62
	v_readlane_b32 s1, v252, 63
	s_and_b64 s[0:1], s[0:1], exec
	s_cselect_b32 s0, s7, 0
	s_add_i32 s7, s2, s0
	v_readlane_b32 s0, v253, 60
	s_addk_i32 s7, 0x3100
	v_mbcnt_lo_u32_b32 v0, -1, 0
	v_mbcnt_hi_u32_b32 v0, -1, v0
	s_add_i32 s29, s0, s2
	v_add_u32_e32 v0, s75, v0
	s_cmp_ge_i32 s29, s7
	s_cbranch_scc1 .LBB0_1601
	s_mul_hi_i32 s0, s29, 0x5397829d
	s_lshr_b32 s1, s0, 31
	s_ashr_i32 s0, s0, 11
	s_add_i32 s26, s0, s1
	s_mul_i32 s1, s26, 0x1880
	s_ashr_i32 s30, s26, 1
	s_and_b32 s0, s26, 1
	s_sub_i32 s1, s29, s1
	s_ashr_i32 s27, s26, 31
	s_mul_i32 s10, s26, 0x1880000
	v_readlane_b32 s11, v253, 5
	s_mul_hi_i32 s2, s26, 0x1880000
	s_add_u32 s22, s11, s10
	v_readlane_b32 s10, v253, 6
	s_addc_u32 s23, s10, s2
	s_mul_i32 s10, s26, 0x11000
	v_readlane_b32 s11, v253, 7
	s_mul_hi_i32 s2, s26, 0x11000
	s_add_u32 s24, s11, s10
	v_readlane_b32 s10, v253, 8
	s_addc_u32 s25, s10, s2
	s_cmpk_gt_i32 s1, 0x5ff
	s_mov_b64 s[46:47], -1
	s_cbranch_scc0 .LBB0_1558
	s_cmpk_gt_u32 s1, 0x7ff
	s_cbranch_scc0 .LBB0_1555
	s_mov_b64 s[18:19], -1
	s_cmpk_gt_u32 s1, 0x12ff
	s_mul_hi_i32 s2, s26, 0xb00000
	s_mul_i32 s13, s26, 0xb00000
	s_cbranch_scc0 .LBB0_1553
	v_readlane_b32 s56, v253, 26
	v_readlane_b32 s57, v253, 27
	s_add_u32 s10, s56, s13
	s_addc_u32 s11, s57, s2
	s_add_u32 s14, s22, 0x1300000
	s_addc_u32 s15, s23, 0
	s_lshl_b32 s16, s1, 1
	s_lshl_b32 s12, s1, 5
	s_and_b32 s16, s16, 0x7fffffc0
	v_readlane_b32 s58, v253, 28
	v_readlane_b32 s59, v253, 29
	v_readlane_b32 s60, v253, 30
	v_readlane_b32 s61, v253, 31
	v_readlane_b32 s62, v253, 32
	v_readlane_b32 s63, v253, 33
	s_and_b32 s12, s12, 0x3e0
	s_addk_i32 s16, 0xda00
	s_mov_b64 s[18:19], 0

; __device__ __forceinline__ PItem p0_decode(const Args& a, int it) {
;     constexpr int I_IN = 16 * 96, I_OUT = 16 * 32, I_W1 = 16 * 88, I_W2 = 44 * 32, I_LAYER = I_IN + I_OUT + 2 * I_W1 + I_W2;
;     const int l = it / I_LAYER, e = l >> 1, odd = l & 1; int r = it % I_LAYER;
;     unsigned char* wl = a.ws + WS_W + (size_t)l * W_LAYER; float* cv = (float*)(a.ws + WS_CVEC) + (size_t)l * CVEC_LAYER;
;     PItem p;
;     if (r < I_IN) { const int kb = r / 96, nb = r % 96; p.W = (odd ? a.in[13] : a.in[5]) + (size_t)e * D * EIN; p.N = EIN; p.K = D; p.g = l > 0 ? a.in[21] + (size_t)(l - 1) * D : nullptr; p.be = l > 0 ? a.in[22] + (size_t)(l - 1) * D : nullptr;
;         p.WT = (bf16*)(wl + W_IN); p.drow0 = in_dst_row(32 * nb, odd); p.k0 = 64 * kb; p.n0 = 32 * nb; p.c1 = cv; p.c2 = cv + EIN; return p; } r -= I_IN;
;     if (r < I_OUT) { const int kb = r / 32, nb = r % 32; p.W = (odd ? a.in[15] : a.in[6]) + (size_t)e * D * D; p.N = D; p.K = D; p.g = nullptr; p.be = nullptr;
;         p.WT = (bf16*)(wl + W_OUT); p.drow0 = 32 * nb; p.k0 = 64 * kb; p.n0 = 32 * nb; p.c1 = nullptr; p.c2 = nullptr; return p; } r -= I_OUT;
;     if (r < 2 * I_W1) { const int second = r >= I_W1; if (second) r -= I_W1; const int kb = r / 88, nb = r % 88, n0 = 32 * nb; p.W = (second ? a.in[17] : a.in[16]) + (size_t)l * D * DFF; p.N = DFF; p.K = D;
;         p.g = a.in[19] + (size_t)l * D; p.be = a.in[20] + (size_t)l * D; p.WT = (bf16*)(wl + W_13); p.drow0 = 256 * (n0 >> 7) + (second ? 128 : 0) + (n0 & 127); p.k0 = 64 * kb; p.n0 = n0; p.c1 = cv + 2 * EIN; p.c2 = cv + 2 * EIN + NUP; return p; } r -= 2 * I_W1;
; __global__ void __launch_bounds__(NWAVES * 64, 2) mk_fwd(Args args) {
;     ...
;                   if (l < 3) { if (mfirst > 0) { if ((int)blockIdx.x < mfirst) { p_convert_tail(F, args, (l + 1) * P_ILAYER, (l + 2) * P_ILAYER - ((F.G == 256) ? (l == 0 ? 768 : 1792) : 0), (int)blockIdx.x, mfirst); if (l == 0) p_state_copies_tail(F, args, (int)blockIdx.x, mfirst); } }
;                   else { p_convert_tail(F, args, (l + 1) * P_ILAYER, (l + 2) * P_ILAYER - ((F.G == 256) ? (l == 0 ? 768 : 1792) : 0), (int)blockIdx.x, F.G); if (l == 0) p_state_copies_tail(F, args, (int)blockIdx.x, F.G); } } } }
.LBB0_1627:
	s_and_b64 vcc, exec, s[10:11]
	s_cbranch_vccz .LBB0_1707
	v_readlane_b32 s0, v254, 27
	s_cmp_ge_i32 s0, s28
	v_readlane_b32 s1, v254, 28
	s_cbranch_scc1 .LBB0_1707
	v_readlane_b32 s0, v255, 62
	v_readlane_b32 s1, v255, 63
	s_mul_i32 s2, s0, 0x1880
	v_readlane_b32 s0, v255, 53
	v_readlane_b32 s1, v255, 54
	s_and_b64 s[0:1], s[0:1], exec
	s_movk_i32 s0, 0xfb00
	s_cselect_b32 s7, s0, 0xfffff500
	v_readlane_b32 s0, v252, 62
	v_readlane_b32 s1, v252, 63
	s_and_b64 s[0:1], s[0:1], exec
	s_cselect_b32 s0, s7, 0
	s_add_i32 s7, s2, s0
	v_readlane_b32 s0, v253, 60
	s_addk_i32 s7, 0x3100
	v_mbcnt_lo_u32_b32 v0, -1, 0
	v_mbcnt_hi_u32_b32 v0, -1, v0
	s_add_i32 s29, s0, s2
	v_add_u32_e32 v0, s75, v0
	s_cmp_ge_i32 s29, s7
	s_cbranch_scc1 .LBB0_1682
	s_mul_hi_i32 s0, s29, 0x5397829d
	s_lshr_b32 s1, s0, 31
	s_ashr_i32 s0, s0, 11
	s_add_i32 s26, s0, s1
	s_mul_i32 s1, s26, 0x1880
	s_ashr_i32 s30, s26, 1
	s_and_b32 s0, s26, 1
	s_sub_i32 s1, s29, s1
	s_ashr_i32 s27, s26, 31
	s_mul_i32 s10, s26, 0x1880000
	v_readlane_b32 s11, v253, 5
	s_mul_hi_i32 s2, s26, 0x1880000
	s_add_u32 s22, s11, s10
	v_readlane_b32 s10, v253, 6
	s_addc_u32 s23, s10, s2
	s_mul_i32 s10, s26, 0x11000
	v_readlane_b32 s11, v253, 7
	s_mul_hi_i32 s2, s26, 0x11000
	s_add_u32 s24, s11, s10
	v_readlane_b32 s10, v253, 8
	s_addc_u32 s25, s10, s2
	v_readlane_b32 s48, v250, 0
	s_cmpk_gt_i32 s1, 0x5ff
	s_mov_b64 s[46:47], -1
	v_readlane_b32 s49, v250, 1
	s_cbranch_scc0 .LBB0_1639
	s_cmpk_gt_u32 s1, 0x7ff
	s_cbranch_scc0 .LBB0_1636
	s_mov_b64 s[18:19], -1
	s_cmpk_gt_u32 s1, 0x12ff
	s_mul_hi_i32 s2, s26, 0xb00000
	s_mul_i32 s13, s26, 0xb00000
	s_cbranch_scc0 .LBB0_1634
	v_readlane_b32 s56, v253, 26
	v_readlane_b32 s57, v253, 27
	s_add_u32 s10, s56, s13
	s_addc_u32 s11, s57, s2
	s_add_u32 s14, s22, 0x1300000
	s_addc_u32 s15, s23, 0
	s_lshl_b32 s16, s1, 1
	s_lshl_b32 s12, s1, 5
	s_and_b32 s16, s16, 0x7fffffc0
	v_readlane_b32 s58, v253, 28
	v_readlane_b32 s59, v253, 29
	v_readlane_b32 s60, v253, 30
	v_readlane_b32 s61, v253, 31
	v_readlane_b32 s62, v253, 32
	v_readlane_b32 s63, v253, 33
	s_and_b32 s12, s12, 0x3e0
	s_addk_i32 s16, 0xda00
	s_mov_b64 s[18:19], 0
